# pc1_hook_and_epilogue_loads_hoisted
# speedup vs baseline: 1.0054x; 1.0032x over previous
; __device__ __forceinline__ float bf_lo(unsigned w) { return __uint_as_float(w << 16); }
; __device__ __forceinline__ float bf_hi(unsigned w) { return __uint_as_float(w & 0xffff0000u); }
; template <class Epi, class Sched>
; __device__ __forceinline__ void gemm_phase(LAS unsigned char* lds, const Sched& S, const Epi& E, bool natural = false) {
;     ...
;             if constexpr (Epi::MIDHOOK) { if (t == nt / 2) E.mid(acc, cur, wr, wc, fr, fq); }
;     __device__ __forceinline__ void mid(AccT& acc, const Unit& u, int wr, int wc, int fr, int fq) const {
;         unsigned base = (unsigned)((u.pm * 256 + 64 * wr + fr) * 1024 + u.pn * 256 + 64 * wc + 8 * fq) * 2u;
;         asm volatile("" : "+v"(base));
; #pragma unroll
;         for (int ai = 0; ai < 2; ++ai)
; #pragma unroll
;             for (int m = 0; m < 4; ++m) {
; #pragma unroll
;                 for (int bj = 0; bj < 2; ++bj) {
;                     const unsigned off = base + (unsigned)((128 * ai + 16 * m) * 1024 + 32 * bj) * 2u;
;                     const u32x4 a = *(const u32x4*)((const char*)GA + off);
;                     f32x4 r0, r1;
;                     r0[0] = bf_lo(a.x); r0[1] = bf_hi(a.x); r0[2] = bf_lo(a.y); r0[3] = bf_hi(a.y);
;                     r1[0] = bf_lo(a.z); r1[1] = bf_hi(a.z); r1[2] = bf_lo(a.w); r1[3] = bf_hi(a.w);
;                     acc[ai][bj][m][0] *= r0; acc[ai][bj][m][1] *= r1;
;                 }
;             }
;     }
.LBB0_492:
	s_cmpk_lg_i32 s26, 0x400
	s_cbranch_scc1 .LBB0_491
	v_mov_b32_e32 v189, v176
	v_add_u32_e32 v224, 0x8000, v189
	v_add_u32_e32 v225, 0x10000, v189
	v_add_u32_e32 v226, 0x18000, v189
	v_add_u32_e32 v227, 0x40000, v189
	v_add_u32_e32 v228, 0x48000, v189
	v_add_u32_e32 v229, 0x50000, v189
	v_add_u32_e32 v230, 0x58000, v189
	global_load_dwordx4 v[128:131], v189, s[62:63]
	global_load_dwordx4 v[132:135], v189, s[62:63] offset:64
	global_load_dwordx4 v[136:139], v224, s[62:63]
	global_load_dwordx4 v[140:143], v224, s[62:63] offset:64
	global_load_dwordx4 v[144:147], v225, s[62:63]
	global_load_dwordx4 v[148:151], v225, s[62:63] offset:64
	global_load_dwordx4 v[152:155], v226, s[62:63]
	global_load_dwordx4 v[156:159], v226, s[62:63] offset:64
	global_load_dwordx4 v[192:195], v227, s[62:63]
	global_load_dwordx4 v[196:199], v227, s[62:63] offset:64
	global_load_dwordx4 v[200:203], v228, s[62:63]
	global_load_dwordx4 v[204:207], v228, s[62:63] offset:64
	global_load_dwordx4 v[208:211], v229, s[62:63]
	global_load_dwordx4 v[212:215], v229, s[62:63] offset:64
	global_load_dwordx4 v[216:219], v230, s[62:63]
	global_load_dwordx4 v[220:223], v230, s[62:63] offset:64
	s_waitcnt vmcnt(15)
	v_lshlrev_b32_e32 v234, 16, v128
	v_and_b32_e32 v235, 0xffff0000, v128
	v_lshlrev_b32_e32 v236, 16, v129
	v_and_b32_e32 v237, 0xffff0000, v129
	v_lshlrev_b32_e32 v238, 16, v130
	v_and_b32_e32 v239, 0xffff0000, v130
	v_lshlrev_b32_e32 v240, 16, v131
	v_and_b32_e32 v241, 0xffff0000, v131
	v_pk_mul_f32 v[124:125], v[124:125], v[234:235]
	v_pk_mul_f32 v[126:127], v[126:127], v[236:237]
	v_pk_mul_f32 v[120:121], v[120:121], v[238:239]
	v_pk_mul_f32 v[122:123], v[122:123], v[240:241]
	s_waitcnt vmcnt(14)
	v_lshlrev_b32_e32 v234, 16, v132
	v_and_b32_e32 v235, 0xffff0000, v132
	v_lshlrev_b32_e32 v236, 16, v133
	v_and_b32_e32 v237, 0xffff0000, v133
	v_lshlrev_b32_e32 v238, 16, v134
	v_and_b32_e32 v239, 0xffff0000, v134
	v_lshlrev_b32_e32 v240, 16, v135
	v_and_b32_e32 v241, 0xffff0000, v135
	v_pk_mul_f32 v[116:117], v[116:117], v[234:235]
	v_pk_mul_f32 v[118:119], v[118:119], v[236:237]
	v_pk_mul_f32 v[112:113], v[112:113], v[238:239]
	v_pk_mul_f32 v[114:115], v[114:115], v[240:241]
	s_waitcnt vmcnt(13)
	v_lshlrev_b32_e32 v234, 16, v136
	v_and_b32_e32 v235, 0xffff0000, v136
	v_lshlrev_b32_e32 v236, 16, v137
	v_and_b32_e32 v237, 0xffff0000, v137
	v_lshlrev_b32_e32 v238, 16, v138
	v_and_b32_e32 v239, 0xffff0000, v138
	v_lshlrev_b32_e32 v240, 16, v139
	v_and_b32_e32 v241, 0xffff0000, v139
	v_pk_mul_f32 v[108:109], v[108:109], v[234:235]
	v_pk_mul_f32 v[110:111], v[110:111], v[236:237]
	v_pk_mul_f32 v[104:105], v[104:105], v[238:239]
	v_pk_mul_f32 v[106:107], v[106:107], v[240:241]
	s_waitcnt vmcnt(12)
	v_lshlrev_b32_e32 v234, 16, v140
	v_and_b32_e32 v235, 0xffff0000, v140
	v_lshlrev_b32_e32 v236, 16, v141
	v_and_b32_e32 v237, 0xffff0000, v141
	v_lshlrev_b32_e32 v238, 16, v142
	v_and_b32_e32 v239, 0xffff0000, v142
	v_lshlrev_b32_e32 v240, 16, v143
	v_and_b32_e32 v241, 0xffff0000, v143
	v_pk_mul_f32 v[100:101], v[100:101], v[234:235]
	v_pk_mul_f32 v[102:103], v[102:103], v[236:237]
	v_pk_mul_f32 v[96:97], v[96:97], v[238:239]
	v_pk_mul_f32 v[98:99], v[98:99], v[240:241]
	s_waitcnt vmcnt(11)
	v_lshlrev_b32_e32 v234, 16, v144
	v_and_b32_e32 v235, 0xffff0000, v144
	v_lshlrev_b32_e32 v236, 16, v145
	v_and_b32_e32 v237, 0xffff0000, v145
	v_lshlrev_b32_e32 v238, 16, v146
	v_and_b32_e32 v239, 0xffff0000, v146
	v_lshlrev_b32_e32 v240, 16, v147
	v_and_b32_e32 v241, 0xffff0000, v147
	v_pk_mul_f32 v[92:93], v[92:93], v[234:235]
	v_pk_mul_f32 v[94:95], v[94:95], v[236:237]
	v_pk_mul_f32 v[88:89], v[88:89], v[238:239]
	v_pk_mul_f32 v[90:91], v[90:91], v[240:241]
	s_waitcnt vmcnt(10)
	v_lshlrev_b32_e32 v234, 16, v148
	v_and_b32_e32 v235, 0xffff0000, v148
	v_lshlrev_b32_e32 v236, 16, v149
	v_and_b32_e32 v237, 0xffff0000, v149
	v_lshlrev_b32_e32 v238, 16, v150
	v_and_b32_e32 v239, 0xffff0000, v150
	v_lshlrev_b32_e32 v240, 16, v151
	v_and_b32_e32 v241, 0xffff0000, v151
	v_pk_mul_f32 v[84:85], v[84:85], v[234:235]
	v_pk_mul_f32 v[86:87], v[86:87], v[236:237]
	v_pk_mul_f32 v[80:81], v[80:81], v[238:239]
	v_pk_mul_f32 v[82:83], v[82:83], v[240:241]
	s_waitcnt vmcnt(9)
	v_lshlrev_b32_e32 v234, 16, v152
	v_and_b32_e32 v235, 0xffff0000, v152
	v_lshlrev_b32_e32 v236, 16, v153
	v_and_b32_e32 v237, 0xffff0000, v153
	v_lshlrev_b32_e32 v238, 16, v154
	v_and_b32_e32 v239, 0xffff0000, v154
	v_lshlrev_b32_e32 v240, 16, v155
	v_and_b32_e32 v241, 0xffff0000, v155
	v_pk_mul_f32 v[76:77], v[76:77], v[234:235]
	v_pk_mul_f32 v[78:79], v[78:79], v[236:237]
	v_pk_mul_f32 v[72:73], v[72:73], v[238:239]
	v_pk_mul_f32 v[74:75], v[74:75], v[240:241]
	s_waitcnt vmcnt(8)
; __device__ __forceinline__ float bf_lo(unsigned w) { return __uint_as_float(w << 16); }
; __device__ __forceinline__ float bf_hi(unsigned w) { return __uint_as_float(w & 0xffff0000u); }
;     __device__ __forceinline__ void mid(AccT& acc, const Unit& u, int wr, int wc, int fr, int fq) const {
;         unsigned base = (unsigned)((u.pm * 256 + 64 * wr + fr) * 1024 + u.pn * 256 + 64 * wc + 8 * fq) * 2u;
;         asm volatile("" : "+v"(base));
; #pragma unroll
;         for (int ai = 0; ai < 2; ++ai)
; #pragma unroll
;             for (int m = 0; m < 4; ++m) {
; #pragma unroll
;                 for (int bj = 0; bj < 2; ++bj) {
;                     const unsigned off = base + (unsigned)((128 * ai + 16 * m) * 1024 + 32 * bj) * 2u;
;                     const u32x4 a = *(const u32x4*)((const char*)GA + off);
;                     f32x4 r0, r1;
;                     r0[0] = bf_lo(a.x); r0[1] = bf_hi(a.x); r0[2] = bf_lo(a.y); r0[3] = bf_hi(a.y);
;                     r1[0] = bf_lo(a.z); r1[1] = bf_hi(a.z); r1[2] = bf_lo(a.w); r1[3] = bf_hi(a.w);
;                     acc[ai][bj][m][0] *= r0; acc[ai][bj][m][1] *= r1;
;                 }
;             }
;     }
	v_lshlrev_b32_e32 v234, 16, v156
	v_and_b32_e32 v235, 0xffff0000, v156
	v_lshlrev_b32_e32 v236, 16, v157
	v_and_b32_e32 v237, 0xffff0000, v157
	v_lshlrev_b32_e32 v238, 16, v158
	v_and_b32_e32 v239, 0xffff0000, v158
	v_lshlrev_b32_e32 v240, 16, v159
	v_and_b32_e32 v241, 0xffff0000, v159
	v_pk_mul_f32 v[68:69], v[68:69], v[234:235]
	v_pk_mul_f32 v[70:71], v[70:71], v[236:237]
	v_pk_mul_f32 v[64:65], v[64:65], v[238:239]
	v_pk_mul_f32 v[66:67], v[66:67], v[240:241]
	s_waitcnt vmcnt(7)
	v_lshlrev_b32_e32 v234, 16, v192
	v_and_b32_e32 v235, 0xffff0000, v192
	v_lshlrev_b32_e32 v236, 16, v193
	v_and_b32_e32 v237, 0xffff0000, v193
	v_lshlrev_b32_e32 v238, 16, v194
	v_and_b32_e32 v239, 0xffff0000, v194
	v_lshlrev_b32_e32 v240, 16, v195
	v_and_b32_e32 v241, 0xffff0000, v195
	v_pk_mul_f32 v[60:61], v[60:61], v[234:235]
	v_pk_mul_f32 v[62:63], v[62:63], v[236:237]
	v_pk_mul_f32 v[56:57], v[56:57], v[238:239]
	v_pk_mul_f32 v[58:59], v[58:59], v[240:241]
	s_waitcnt vmcnt(6)
	v_lshlrev_b32_e32 v234, 16, v196
	v_and_b32_e32 v235, 0xffff0000, v196
	v_lshlrev_b32_e32 v236, 16, v197
	v_and_b32_e32 v237, 0xffff0000, v197
	v_lshlrev_b32_e32 v238, 16, v198
	v_and_b32_e32 v239, 0xffff0000, v198
	v_lshlrev_b32_e32 v240, 16, v199
	v_and_b32_e32 v241, 0xffff0000, v199
	v_pk_mul_f32 v[52:53], v[52:53], v[234:235]
	v_pk_mul_f32 v[54:55], v[54:55], v[236:237]
	v_pk_mul_f32 v[48:49], v[48:49], v[238:239]
	v_pk_mul_f32 v[50:51], v[50:51], v[240:241]
	s_waitcnt vmcnt(5)
	v_lshlrev_b32_e32 v234, 16, v200
	v_and_b32_e32 v235, 0xffff0000, v200
	v_lshlrev_b32_e32 v236, 16, v201
	v_and_b32_e32 v237, 0xffff0000, v201
	v_lshlrev_b32_e32 v238, 16, v202
	v_and_b32_e32 v239, 0xffff0000, v202
	v_lshlrev_b32_e32 v240, 16, v203
	v_and_b32_e32 v241, 0xffff0000, v203
	v_pk_mul_f32 v[44:45], v[44:45], v[234:235]
	v_pk_mul_f32 v[46:47], v[46:47], v[236:237]
	v_pk_mul_f32 v[40:41], v[40:41], v[238:239]
	v_pk_mul_f32 v[42:43], v[42:43], v[240:241]
	s_waitcnt vmcnt(4)
	v_lshlrev_b32_e32 v234, 16, v204
	v_and_b32_e32 v235, 0xffff0000, v204
	v_lshlrev_b32_e32 v236, 16, v205
	v_and_b32_e32 v237, 0xffff0000, v205
	v_lshlrev_b32_e32 v238, 16, v206
	v_and_b32_e32 v239, 0xffff0000, v206
	v_lshlrev_b32_e32 v240, 16, v207
	v_and_b32_e32 v241, 0xffff0000, v207
	v_pk_mul_f32 v[36:37], v[36:37], v[234:235]
	v_pk_mul_f32 v[38:39], v[38:39], v[236:237]
	v_pk_mul_f32 v[32:33], v[32:33], v[238:239]
	v_pk_mul_f32 v[34:35], v[34:35], v[240:241]
	s_waitcnt vmcnt(3)
	v_lshlrev_b32_e32 v234, 16, v208
	v_and_b32_e32 v235, 0xffff0000, v208
	v_lshlrev_b32_e32 v236, 16, v209
	v_and_b32_e32 v237, 0xffff0000, v209
	v_lshlrev_b32_e32 v238, 16, v210
	v_and_b32_e32 v239, 0xffff0000, v210
	v_lshlrev_b32_e32 v240, 16, v211
	v_and_b32_e32 v241, 0xffff0000, v211
	v_pk_mul_f32 v[28:29], v[28:29], v[234:235]
	v_pk_mul_f32 v[30:31], v[30:31], v[236:237]
	v_pk_mul_f32 v[24:25], v[24:25], v[238:239]
	v_pk_mul_f32 v[26:27], v[26:27], v[240:241]
	s_waitcnt vmcnt(2)
	v_lshlrev_b32_e32 v234, 16, v212
	v_and_b32_e32 v235, 0xffff0000, v212
	v_lshlrev_b32_e32 v236, 16, v213
	v_and_b32_e32 v237, 0xffff0000, v213
	v_lshlrev_b32_e32 v238, 16, v214
	v_and_b32_e32 v239, 0xffff0000, v214
	v_lshlrev_b32_e32 v240, 16, v215
	v_and_b32_e32 v241, 0xffff0000, v215
	v_pk_mul_f32 v[20:21], v[20:21], v[234:235]
	v_pk_mul_f32 v[22:23], v[22:23], v[236:237]
	v_pk_mul_f32 v[16:17], v[16:17], v[238:239]
	v_pk_mul_f32 v[18:19], v[18:19], v[240:241]
	s_waitcnt vmcnt(1)
	v_lshlrev_b32_e32 v234, 16, v216
	v_and_b32_e32 v235, 0xffff0000, v216
	v_lshlrev_b32_e32 v236, 16, v217
	v_and_b32_e32 v237, 0xffff0000, v217
	v_lshlrev_b32_e32 v238, 16, v218
	v_and_b32_e32 v239, 0xffff0000, v218
	v_lshlrev_b32_e32 v240, 16, v219
	v_and_b32_e32 v241, 0xffff0000, v219
	v_pk_mul_f32 v[12:13], v[12:13], v[234:235]
	v_pk_mul_f32 v[14:15], v[14:15], v[236:237]
	v_pk_mul_f32 v[8:9], v[8:9], v[238:239]
	v_pk_mul_f32 v[10:11], v[10:11], v[240:241]
	s_waitcnt vmcnt(0)
	v_lshlrev_b32_e32 v234, 16, v220
	v_and_b32_e32 v235, 0xffff0000, v220
	v_lshlrev_b32_e32 v236, 16, v221
	v_and_b32_e32 v237, 0xffff0000, v221
	v_lshlrev_b32_e32 v238, 16, v222
	v_and_b32_e32 v239, 0xffff0000, v222
	v_lshlrev_b32_e32 v240, 16, v223
	v_and_b32_e32 v241, 0xffff0000, v223
	v_pk_mul_f32 v[4:5], v[4:5], v[234:235]
	v_pk_mul_f32 v[6:7], v[6:7], v[236:237]
	v_pk_mul_f32 v[0:1], v[0:1], v[238:239]
	v_pk_mul_f32 v[2:3], v[2:3], v[240:241]
	s_branch .LBB0_491

; __device__ __forceinline__ unsigned cvt_pk_bf16(float lo, float hi) { const f32x2_t v = {lo, hi}; const bf16x2_t r = __builtin_convertvector(v, bf16x2_t); return __builtin_bit_cast(unsigned, r); }
; __device__ __forceinline__ float bf_lo(unsigned w) { return __uint_as_float(w << 16); }
; __device__ __forceinline__ float bf_hi(unsigned w) { return __uint_as_float(w & 0xffff0000u); }
;     __device__ __forceinline__ void operator()(AccT& acc, const Unit& u, int wr, int wc, int fr, int fq) const {
;         unsigned base = (unsigned)((u.pm * 256 + 64 * wr + fr) * 1024 + u.pn * 256 + 64 * wc + 8 * fq) * 2u;
;         asm volatile("" : "+v"(base));
;         u32x4 sv[2][4][2];
; #pragma unroll
;         for (int ai = 0; ai < 2; ++ai)
; #pragma unroll
;             for (int m = 0; m < 4; ++m)
; #pragma unroll
;                 for (int bj = 0; bj < 2; ++bj) sv[ai][m][bj] = *(const u32x4*)((const char*)GB + base + (unsigned)((128 * ai + 16 * m) * 1024 + 32 * bj) * 2u);
; #pragma unroll
;         for (int ai = 0; ai < 2; ++ai)
; #pragma unroll
;             for (int m = 0; m < 4; ++m) {
; #pragma unroll
;                 for (int bj = 0; bj < 2; ++bj) {
;                     const unsigned off = base + (unsigned)((128 * ai + 16 * m) * 1024 + 32 * bj) * 2u;
;                     const u32x4 b = sv[ai][m][bj];
;                     const f32x4 x0 = acc[ai][bj][m][0], x1 = acc[ai][bj][m][1];
;                     u32x4 o; o.x = cvt_pk_bf16(x0[0] * bf_lo(b.x), x0[1] * bf_hi(b.x)); o.y = cvt_pk_bf16(x0[2] * bf_lo(b.y), x0[3] * bf_hi(b.y));
;                     o.z = cvt_pk_bf16(x1[0] * bf_lo(b.z), x1[1] * bf_hi(b.z)); o.w = cvt_pk_bf16(x1[2] * bf_lo(b.w), x1[3] * bf_hi(b.w));
;                     *(u32x4*)((char*)MG + off) = o;
;                 }
;             }
;     }
.LBB0_496:
	global_load_dwordx4 v[192:195], v176, s[8:9]
	global_load_dwordx4 v[196:199], v176, s[8:9] offset:64
	v_lshl_add_u64 v[128:129], s[8:9], 0, v[176:177]
	v_add_co_u32_e32 v130, vcc, 0x8000, v128
	s_nop 1
	v_add_u32_e32 v189, 64, v176
	v_addc_co_u32_e32 v131, vcc, 0, v129, vcc
	global_load_dwordx4 v[200:203], v[130:131], off
	global_load_dwordx4 v[204:207], v[130:131], off offset:64
	v_add_co_u32_e32 v132, vcc, s44, v128
	s_nop 1
	v_addc_co_u32_e32 v133, vcc, 0, v129, vcc
	global_load_dwordx4 v[208:211], v[132:133], off
	global_load_dwordx4 v[212:215], v[132:133], off offset:64
	v_add_co_u32_e32 v130, vcc, s48, v128
	s_nop 1
	v_addc_co_u32_e32 v131, vcc, 0, v129, vcc
	global_load_dwordx4 v[216:219], v[130:131], off
	global_load_dwordx4 v[160:163], v[130:131], off offset:64
	v_add_co_u32_e32 v132, vcc, s50, v128
	s_nop 1
	v_addc_co_u32_e32 v133, vcc, 0, v129, vcc
	global_load_dwordx4 v[156:159], v[132:133], off
	global_load_dwordx4 v[152:155], v[132:133], off offset:64
	v_add_co_u32_e32 v130, vcc, s51, v128
	s_nop 1
	v_addc_co_u32_e32 v131, vcc, 0, v129, vcc
	global_load_dwordx4 v[148:151], v[130:131], off
	global_load_dwordx4 v[144:147], v[130:131], off offset:64
	v_add_co_u32_e32 v132, vcc, s52, v128
	s_nop 1
	v_addc_co_u32_e32 v133, vcc, 0, v129, vcc
	global_load_dwordx4 v[140:143], v[132:133], off
	global_load_dwordx4 v[136:139], v[132:133], off offset:64
	v_add_co_u32_e32 v128, vcc, s53, v128
	s_nop 1
	v_addc_co_u32_e32 v129, vcc, 0, v129, vcc
	global_load_dwordx4 v[132:135], v[128:129], off
	global_load_dwordx4 v[128:131], v[128:129], off offset:64
	s_waitcnt vmcnt(12)
	v_lshlrev_b32_e32 v222, 16, v194
	v_and_b32_e32 v223, 0xffff0000, v194
	v_lshlrev_b32_e32 v194, 16, v195
	v_and_b32_e32 v195, 0xffff0000, v195
	v_lshlrev_b32_e32 v226, 16, v198
	v_and_b32_e32 v227, 0xffff0000, v198
	v_lshlrev_b32_e32 v224, 16, v196
	v_and_b32_e32 v225, 0xffff0000, v196
	v_lshlrev_b32_e32 v196, 16, v197
	v_and_b32_e32 v197, 0xffff0000, v197
	v_lshlrev_b32_e32 v198, 16, v199
	v_and_b32_e32 v199, 0xffff0000, v199
	v_pk_mul_f32 v[122:123], v[122:123], v[194:195]
	v_pk_mul_f32 v[112:113], v[112:113], v[226:227]
	v_pk_mul_f32 v[194:195], v[118:119], v[196:197]
	v_cvt_pk_bf16_f32 v119, v122, v123
	v_cvt_pk_bf16_f32 v122, v112, v113
	v_pk_mul_f32 v[112:113], v[114:115], v[198:199]
	v_cvt_pk_bf16_f32 v123, v112, v113
	v_lshlrev_b32_e32 v112, 16, v200
	v_and_b32_e32 v113, 0xffff0000, v200
	v_pk_mul_f32 v[108:109], v[108:109], v[112:113]
	v_lshlrev_b32_e32 v112, 16, v201
	v_and_b32_e32 v113, 0xffff0000, v201
	v_pk_mul_f32 v[110:111], v[110:111], v[112:113]
	v_cvt_pk_bf16_f32 v108, v108, v109
	v_cvt_pk_bf16_f32 v109, v110, v111
	v_lshlrev_b32_e32 v110, 16, v202
	v_and_b32_e32 v111, 0xffff0000, v202
	v_pk_mul_f32 v[104:105], v[104:105], v[110:111]
	v_cvt_pk_bf16_f32 v110, v104, v105
	v_lshlrev_b32_e32 v104, 16, v203
	v_and_b32_e32 v105, 0xffff0000, v203
	v_pk_mul_f32 v[104:105], v[106:107], v[104:105]
	v_lshlrev_b32_e32 v220, 16, v192
	v_cvt_pk_bf16_f32 v111, v104, v105
	v_lshlrev_b32_e32 v104, 16, v204
	v_and_b32_e32 v105, 0xffff0000, v204
	v_pk_mul_f32 v[100:101], v[100:101], v[104:105]
	v_lshlrev_b32_e32 v104, 16, v205
	v_and_b32_e32 v105, 0xffff0000, v205
	v_pk_mul_f32 v[102:103], v[102:103], v[104:105]
	v_cvt_pk_bf16_f32 v100, v100, v101
	v_cvt_pk_bf16_f32 v101, v102, v103
	v_lshlrev_b32_e32 v102, 16, v206
	v_and_b32_e32 v103, 0xffff0000, v206
	v_pk_mul_f32 v[96:97], v[96:97], v[102:103]
	v_and_b32_e32 v221, 0xffff0000, v192
	v_cvt_pk_bf16_f32 v102, v96, v97
	v_lshlrev_b32_e32 v96, 16, v207
	v_and_b32_e32 v97, 0xffff0000, v207
	v_pk_mul_f32 v[96:97], v[98:99], v[96:97]
	v_lshlrev_b32_e32 v192, 16, v193
	v_cvt_pk_bf16_f32 v103, v96, v97
	s_waitcnt vmcnt(11)
	v_lshlrev_b32_e32 v96, 16, v208
	v_and_b32_e32 v97, 0xffff0000, v208
	v_pk_mul_f32 v[92:93], v[92:93], v[96:97]
	v_lshlrev_b32_e32 v96, 16, v209
	v_and_b32_e32 v97, 0xffff0000, v209
	v_pk_mul_f32 v[94:95], v[94:95], v[96:97]
	v_cvt_pk_bf16_f32 v92, v92, v93
	v_cvt_pk_bf16_f32 v93, v94, v95
	v_lshlrev_b32_e32 v94, 16, v210
	v_and_b32_e32 v95, 0xffff0000, v210
	v_pk_mul_f32 v[88:89], v[88:89], v[94:95]
	v_and_b32_e32 v193, 0xffff0000, v193
	v_cvt_pk_bf16_f32 v94, v88, v89
	v_lshlrev_b32_e32 v88, 16, v211
	v_and_b32_e32 v89, 0xffff0000, v211
	v_pk_mul_f32 v[88:89], v[90:91], v[88:89]
	v_pk_mul_f32 v[124:125], v[124:125], v[220:221]
	v_cvt_pk_bf16_f32 v95, v88, v89
	s_waitcnt vmcnt(10)
	v_lshlrev_b32_e32 v88, 16, v212
	v_and_b32_e32 v89, 0xffff0000, v212
	v_pk_mul_f32 v[84:85], v[84:85], v[88:89]
	v_lshlrev_b32_e32 v88, 16, v213
	v_and_b32_e32 v89, 0xffff0000, v213
	v_pk_mul_f32 v[86:87], v[86:87], v[88:89]
	v_cvt_pk_bf16_f32 v84, v84, v85
	v_cvt_pk_bf16_f32 v85, v86, v87
	v_lshlrev_b32_e32 v86, 16, v214
	v_and_b32_e32 v87, 0xffff0000, v214
	v_pk_mul_f32 v[80:81], v[80:81], v[86:87]
	v_pk_mul_f32 v[126:127], v[126:127], v[192:193]
	v_cvt_pk_bf16_f32 v86, v80, v81
	v_lshlrev_b32_e32 v80, 16, v215
	v_and_b32_e32 v81, 0xffff0000, v215
	v_pk_mul_f32 v[80:81], v[82:83], v[80:81]
	v_pk_mul_f32 v[120:121], v[120:121], v[222:223]
	v_cvt_pk_bf16_f32 v87, v80, v81
	s_waitcnt vmcnt(9)
	v_lshlrev_b32_e32 v80, 16, v216
	v_and_b32_e32 v81, 0xffff0000, v216
	v_pk_mul_f32 v[76:77], v[76:77], v[80:81]
	v_lshlrev_b32_e32 v80, 16, v217
	v_and_b32_e32 v81, 0xffff0000, v217
	v_pk_mul_f32 v[78:79], v[78:79], v[80:81]
	v_cvt_pk_bf16_f32 v76, v76, v77
	v_cvt_pk_bf16_f32 v77, v78, v79
	v_lshlrev_b32_e32 v78, 16, v218
	v_and_b32_e32 v79, 0xffff0000, v218
	v_pk_mul_f32 v[72:73], v[72:73], v[78:79]
	v_pk_mul_f32 v[192:193], v[116:117], v[224:225]
	v_cvt_pk_bf16_f32 v78, v72, v73
	v_lshlrev_b32_e32 v72, 16, v219
	v_and_b32_e32 v73, 0xffff0000, v219
	v_pk_mul_f32 v[72:73], v[74:75], v[72:73]
	v_cvt_pk_bf16_f32 v116, v124, v125
	v_cvt_pk_bf16_f32 v79, v72, v73
	s_waitcnt vmcnt(8)
; __device__ __forceinline__ unsigned cvt_pk_bf16(float lo, float hi) { const f32x2_t v = {lo, hi}; const bf16x2_t r = __builtin_convertvector(v, bf16x2_t); return __builtin_bit_cast(unsigned, r); }
; __device__ __forceinline__ float bf_lo(unsigned w) { return __uint_as_float(w << 16); }
; __device__ __forceinline__ float bf_hi(unsigned w) { return __uint_as_float(w & 0xffff0000u); }
; #define PG8_BAR __builtin_amdgcn_s_barrier()
; template <class Epi, class Sched>
; __device__ __forceinline__ void gemm_phase(LAS unsigned char* lds, const Sched& S, const Epi& E, bool natural = false) {
;     ...
;         if (!has_next) break;
; #pragma unroll
;         for (int a = 0; a < 2; ++a)
; #pragma unroll
;             for (int b = 0; b < 2; ++b)
; #pragma unroll
;                 for (int m = 0; m < 4; ++m)
; #pragma unroll
;                     for (int n = 0; n < 2; ++n) acc[a][b][m][n] = (f32x4){0.f, 0.f, 0.f, 0.f};
;         cur = nxt; cA = nA; cB = nB; ++ui;
;         if (wr == 1) PG8_BAR;
;     __device__ __forceinline__ void operator()(AccT& acc, const Unit& u, int wr, int wc, int fr, int fq) const {
;     ...
;         for (int ai = 0; ai < 2; ++ai)
; #pragma unroll
;             for (int m = 0; m < 4; ++m) {
; #pragma unroll
;                 for (int bj = 0; bj < 2; ++bj) {
;                     const unsigned off = base + (unsigned)((128 * ai + 16 * m) * 1024 + 32 * bj) * 2u;
;                     const u32x4 b = sv[ai][m][bj];
;                     const f32x4 x0 = acc[ai][bj][m][0], x1 = acc[ai][bj][m][1];
;                     u32x4 o; o.x = cvt_pk_bf16(x0[0] * bf_lo(b.x), x0[1] * bf_hi(b.x)); o.y = cvt_pk_bf16(x0[2] * bf_lo(b.y), x0[3] * bf_hi(b.y));
;                     o.z = cvt_pk_bf16(x1[0] * bf_lo(b.z), x1[1] * bf_hi(b.z)); o.w = cvt_pk_bf16(x1[2] * bf_lo(b.w), x1[3] * bf_hi(b.w));
;                     *(u32x4*)((char*)MG + off) = o;
;                 }
;             }
;     }
	v_lshlrev_b32_e32 v72, 16, v160
	v_and_b32_e32 v73, 0xffff0000, v160
	v_pk_mul_f32 v[68:69], v[68:69], v[72:73]
	v_lshlrev_b32_e32 v72, 16, v161
	v_and_b32_e32 v73, 0xffff0000, v161
	v_pk_mul_f32 v[70:71], v[70:71], v[72:73]
	v_cvt_pk_bf16_f32 v68, v68, v69
	v_cvt_pk_bf16_f32 v69, v70, v71
	v_lshlrev_b32_e32 v70, 16, v162
	v_and_b32_e32 v71, 0xffff0000, v162
	v_pk_mul_f32 v[64:65], v[64:65], v[70:71]
	v_cvt_pk_bf16_f32 v117, v126, v127
	v_cvt_pk_bf16_f32 v70, v64, v65
	v_lshlrev_b32_e32 v64, 16, v163
	v_and_b32_e32 v65, 0xffff0000, v163
	v_pk_mul_f32 v[64:65], v[66:67], v[64:65]
	v_cvt_pk_bf16_f32 v118, v120, v121
	v_cvt_pk_bf16_f32 v71, v64, v65
	s_waitcnt vmcnt(7)
	v_lshlrev_b32_e32 v64, 16, v156
	v_and_b32_e32 v65, 0xffff0000, v156
	v_pk_mul_f32 v[60:61], v[60:61], v[64:65]
	v_lshlrev_b32_e32 v64, 16, v157
	v_and_b32_e32 v65, 0xffff0000, v157
	v_pk_mul_f32 v[62:63], v[62:63], v[64:65]
	v_cvt_pk_bf16_f32 v60, v60, v61
	v_cvt_pk_bf16_f32 v61, v62, v63
	v_lshlrev_b32_e32 v62, 16, v158
	v_and_b32_e32 v63, 0xffff0000, v158
	v_pk_mul_f32 v[56:57], v[56:57], v[62:63]
	v_cvt_pk_bf16_f32 v120, v192, v193
	v_cvt_pk_bf16_f32 v62, v56, v57
	v_lshlrev_b32_e32 v56, 16, v159
	v_and_b32_e32 v57, 0xffff0000, v159
	v_pk_mul_f32 v[56:57], v[58:59], v[56:57]
	v_cvt_pk_bf16_f32 v121, v194, v195
	v_cvt_pk_bf16_f32 v63, v56, v57
	s_waitcnt vmcnt(6)
	v_lshlrev_b32_e32 v56, 16, v152
	v_and_b32_e32 v57, 0xffff0000, v152
	v_pk_mul_f32 v[52:53], v[52:53], v[56:57]
	v_lshlrev_b32_e32 v56, 16, v153
	v_and_b32_e32 v57, 0xffff0000, v153
	v_pk_mul_f32 v[54:55], v[54:55], v[56:57]
	v_cvt_pk_bf16_f32 v52, v52, v53
	v_cvt_pk_bf16_f32 v53, v54, v55
	v_lshlrev_b32_e32 v54, 16, v154
	v_and_b32_e32 v55, 0xffff0000, v154
	v_pk_mul_f32 v[48:49], v[48:49], v[54:55]
	v_add_u32_e32 v114, 0x8000, v176
	v_cvt_pk_bf16_f32 v54, v48, v49
	v_lshlrev_b32_e32 v48, 16, v155
	v_and_b32_e32 v49, 0xffff0000, v155
	v_pk_mul_f32 v[48:49], v[50:51], v[48:49]
	v_add_u32_e32 v106, 0x8040, v176
	v_cvt_pk_bf16_f32 v55, v48, v49
	s_waitcnt vmcnt(5)
	v_lshlrev_b32_e32 v48, 16, v148
	v_and_b32_e32 v49, 0xffff0000, v148
	v_pk_mul_f32 v[44:45], v[44:45], v[48:49]
	v_lshlrev_b32_e32 v48, 16, v149
	v_and_b32_e32 v49, 0xffff0000, v149
	v_pk_mul_f32 v[46:47], v[46:47], v[48:49]
	v_cvt_pk_bf16_f32 v44, v44, v45
	v_cvt_pk_bf16_f32 v45, v46, v47
	v_lshlrev_b32_e32 v46, 16, v150
	v_and_b32_e32 v47, 0xffff0000, v150
	v_pk_mul_f32 v[40:41], v[40:41], v[46:47]
	v_add_u32_e32 v98, 0x10000, v176
	v_cvt_pk_bf16_f32 v46, v40, v41
	v_lshlrev_b32_e32 v40, 16, v151
	v_and_b32_e32 v41, 0xffff0000, v151
	v_pk_mul_f32 v[40:41], v[42:43], v[40:41]
	v_add_u32_e32 v90, 0x10040, v176
	v_cvt_pk_bf16_f32 v47, v40, v41
	s_waitcnt vmcnt(4)
	v_lshlrev_b32_e32 v40, 16, v144
	v_and_b32_e32 v41, 0xffff0000, v144
	v_pk_mul_f32 v[36:37], v[36:37], v[40:41]
	v_lshlrev_b32_e32 v40, 16, v145
	v_and_b32_e32 v41, 0xffff0000, v145
	v_pk_mul_f32 v[38:39], v[38:39], v[40:41]
	v_cvt_pk_bf16_f32 v36, v36, v37
	v_cvt_pk_bf16_f32 v37, v38, v39
	v_lshlrev_b32_e32 v38, 16, v146
	v_and_b32_e32 v39, 0xffff0000, v146
	v_pk_mul_f32 v[32:33], v[32:33], v[38:39]
	v_add_u32_e32 v82, 0x18000, v176
	v_cvt_pk_bf16_f32 v38, v32, v33
	v_lshlrev_b32_e32 v32, 16, v147
	v_and_b32_e32 v33, 0xffff0000, v147
	v_pk_mul_f32 v[32:33], v[34:35], v[32:33]
	v_add_u32_e32 v74, 0x18040, v176
	v_cvt_pk_bf16_f32 v39, v32, v33
	s_waitcnt vmcnt(3)
	v_lshlrev_b32_e32 v32, 16, v140
	v_and_b32_e32 v33, 0xffff0000, v140
	v_pk_mul_f32 v[28:29], v[28:29], v[32:33]
	v_lshlrev_b32_e32 v32, 16, v141
	v_and_b32_e32 v33, 0xffff0000, v141
	v_pk_mul_f32 v[30:31], v[30:31], v[32:33]
	v_cvt_pk_bf16_f32 v28, v28, v29
	v_cvt_pk_bf16_f32 v29, v30, v31
	v_lshlrev_b32_e32 v30, 16, v142
	v_and_b32_e32 v31, 0xffff0000, v142
	v_pk_mul_f32 v[24:25], v[24:25], v[30:31]
	v_add_u32_e32 v66, 0x40000, v176
	v_cvt_pk_bf16_f32 v30, v24, v25
	v_lshlrev_b32_e32 v24, 16, v143
	v_and_b32_e32 v25, 0xffff0000, v143
	v_pk_mul_f32 v[24:25], v[26:27], v[24:25]
	v_add_u32_e32 v58, 0x40040, v176
	v_cvt_pk_bf16_f32 v31, v24, v25
	s_waitcnt vmcnt(2)
	v_lshlrev_b32_e32 v24, 16, v136
	v_and_b32_e32 v25, 0xffff0000, v136
	v_pk_mul_f32 v[20:21], v[20:21], v[24:25]
	v_lshlrev_b32_e32 v24, 16, v137
	v_and_b32_e32 v25, 0xffff0000, v137
	v_pk_mul_f32 v[22:23], v[22:23], v[24:25]
	v_cvt_pk_bf16_f32 v20, v20, v21
	v_cvt_pk_bf16_f32 v21, v22, v23
	v_lshlrev_b32_e32 v22, 16, v138
	v_and_b32_e32 v23, 0xffff0000, v138
	v_pk_mul_f32 v[16:17], v[16:17], v[22:23]
	v_add_u32_e32 v50, 0x48000, v176
	v_cvt_pk_bf16_f32 v22, v16, v17
	v_lshlrev_b32_e32 v16, 16, v139
	v_and_b32_e32 v17, 0xffff0000, v139
	v_pk_mul_f32 v[16:17], v[18:19], v[16:17]
	v_add_u32_e32 v42, 0x48040, v176
	v_cvt_pk_bf16_f32 v23, v16, v17
	s_waitcnt vmcnt(1)
	v_lshlrev_b32_e32 v16, 16, v132
	v_and_b32_e32 v17, 0xffff0000, v132
	v_pk_mul_f32 v[12:13], v[12:13], v[16:17]
	v_lshlrev_b32_e32 v16, 16, v133
	v_and_b32_e32 v17, 0xffff0000, v133
	v_pk_mul_f32 v[14:15], v[14:15], v[16:17]
	v_cvt_pk_bf16_f32 v12, v12, v13
	v_cvt_pk_bf16_f32 v13, v14, v15
	v_lshlrev_b32_e32 v14, 16, v134
	v_and_b32_e32 v15, 0xffff0000, v134
	v_pk_mul_f32 v[8:9], v[8:9], v[14:15]
	v_add_u32_e32 v34, 0x50000, v176
	v_cvt_pk_bf16_f32 v14, v8, v9
	v_lshlrev_b32_e32 v8, 16, v135
	v_and_b32_e32 v9, 0xffff0000, v135
	v_pk_mul_f32 v[8:9], v[10:11], v[8:9]
	v_add_u32_e32 v26, 0x50040, v176
	v_cvt_pk_bf16_f32 v15, v8, v9
	s_waitcnt vmcnt(0)
	v_lshlrev_b32_e32 v8, 16, v128
	v_and_b32_e32 v9, 0xffff0000, v128
	v_pk_mul_f32 v[4:5], v[4:5], v[8:9]
	v_lshlrev_b32_e32 v8, 16, v129
	v_and_b32_e32 v9, 0xffff0000, v129
	v_pk_mul_f32 v[6:7], v[6:7], v[8:9]
	v_cvt_pk_bf16_f32 v4, v4, v5
	v_cvt_pk_bf16_f32 v5, v6, v7
	v_lshlrev_b32_e32 v6, 16, v130
	v_and_b32_e32 v7, 0xffff0000, v130
	v_pk_mul_f32 v[0:1], v[0:1], v[6:7]
	v_add_u32_e32 v18, 0x58000, v176
	v_cvt_pk_bf16_f32 v6, v0, v1
	v_lshlrev_b32_e32 v0, 16, v131
	v_and_b32_e32 v1, 0xffff0000, v131
	v_pk_mul_f32 v[0:1], v[2:3], v[0:1]
	v_add_u32_e32 v10, 0x58040, v176
	v_cvt_pk_bf16_f32 v7, v0, v1
	s_andn2_b64 vcc, exec, s[0:1]
	s_mov_b64 s[0:1], -1
	global_store_dwordx4 v176, v[116:119], s[10:11]
	global_store_dwordx4 v189, v[120:123], s[10:11]
	global_store_dwordx4 v114, v[108:111], s[10:11]
	global_store_dwordx4 v106, v[100:103], s[10:11]
	global_store_dwordx4 v98, v[92:95], s[10:11]
	global_store_dwordx4 v90, v[84:87], s[10:11]
	global_store_dwordx4 v82, v[76:79], s[10:11]
	global_store_dwordx4 v74, v[68:71], s[10:11]
	global_store_dwordx4 v66, v[60:63], s[10:11]
	global_store_dwordx4 v58, v[52:55], s[10:11]
	global_store_dwordx4 v50, v[44:47], s[10:11]
	global_store_dwordx4 v42, v[36:39], s[10:11]
	global_store_dwordx4 v34, v[28:31], s[10:11]
	global_store_dwordx4 v26, v[20:23], s[10:11]
	global_store_dwordx4 v18, v[12:15], s[10:11]
	global_store_dwordx4 v10, v[4:7], s[10:11]
	s_cbranch_vccnz .LBB0_487
	s_andn2_b64 vcc, exec, s[6:7]
	s_cbranch_vccnz .LBB0_486
	s_barrier
	s_branch .LBB0_486
